# attn task loop: dropped the vmcnt(1) at the dequeue loop head so the queue atomic issues without waiting for the previous task's store acks
# baseline (speedup 1.0000x reference)
.LBB0_219:
	v_writelane_b32 v254, s4, 46
	v_mov_b32_e32 v2, v216
	v_writelane_b32 v254, s5, 47
	v_cmp_eq_u32_e32 vcc, 0, v2
	s_and_saveexec_b64 s[4:5], vcc
	s_cbranch_execz .LBB0_223
	s_mov_b64 s[8:9], exec
	v_mbcnt_lo_u32_b32 v0, s8, 0
	v_mbcnt_hi_u32_b32 v0, s9, v0
	v_cmp_eq_u32_e32 vcc, 0, v0
	s_and_saveexec_b64 s[6:7], vcc
	s_cbranch_execz .LBB0_222
	s_bcnt1_i32_b64 s0, s[8:9]
	v_readlane_b32 s8, v254, 14
	v_mov_b32_e32 v3, s0
	v_readlane_b32 s9, v254, 15
	s_nop 4
	global_atomic_add v3, v1, v3, s[8:9] sc0
